# GQA/MLA attention half-bodies: 20 packed v_pk_add_f32 split into scalar v_add_f32 pairs (guide 7.5), on the static-priority build
# baseline (speedup 1.0000x reference)
; template <int DUAL, bool BOUND> ...
;     ...
;     if (BOUND) {
;       float ps = 0.f;
; #pragma unroll
;       for (int i = 0; i < 16; ++i) {
;         s0[i] = fexp2(s0[i]);
;         s1[i] = fexp2(s1[i]);
;         ps += s0[i] + s1[i];
;       }
;       l += ps;
;     } else {
;       float mx = fmaxf(s0[0], s1[0]);
; #pragma unroll
;       for (int i = 1; i < 16; ++i) mx = fmaxf(mx, fmaxf(s0[i], s1[i]));
;       mx = fmaxf(mx, xhalf(mx));
;       const float mnew = fmaxf(m, mx);
;       const float alpha = fexp2(m - mnew);
;       m = mnew;
;       float ps = 0.f;
; #pragma unroll
;       for (int i = 0; i < 16; ++i) {
;         s0[i] = fexp2(s0[i] - mnew);
;         s1[i] = fexp2(s1[i] - mnew);
;         ps += s0[i] + s1[i];
;       }
;       l = l * alpha + ps;
; #pragma unroll
;       for (int i = 0; i < 16; ++i) { o0[i] *= alpha; o1[i] *= alpha; }
;     }
;     const char* vb0 = cur + A_VOFF + r * V_ROW + hf * 128 + 16 * h;
; #pragma unroll
;     for (int kb = 0; kb < 2; ++kb)
; #pragma unroll
;       for (int s = 0; s < 2; ++s) {
;         uint4 pu;
;     ...
;     for (int hf = 0; hf < 2; ++hf) {
;       if (hf == 1) gload_v(more ? t + 1 : t);
;       const char* kb0 = cur + (hf * 64 + r) * KSTR + h * 16;
;       f32x16 s0, s1;
;       const float rel = (float)(qpos - t * 128 - hf * 64 - 4 * h);
; #pragma unroll
;       for (int st = 0; st < 2; ++st) {
;         constexpr int NCS = (DUAL == 1) ? 2 : 1;
;         bf16x8 ka[NCS][2], kb[NCS][2];
;         __builtin_amdgcn_sched_barrier(0);
; #pragma unroll
;         for (int cc = 0; cc < NCS; ++cc) {
;           const int c = (DUAL == 1) ? cc : st;
; #pragma unroll
;           for (int ks = 0; ks < 2; ++ks) {
;             ka[cc][ks] = *(const bf16x8*)(kb0 + c * 64 + ks * 32);
;             kb[cc][ks] = *(const bf16x8*)(kb0 + 32 * KSTR + c * 64 + ks * 32);
;           }
;         }
;         __builtin_amdgcn_sched_barrier(0);
; #pragma unroll
;         for (int i = 0; i < 16; ++i) { s0[i] = 0.f; s1[i] = 0.f; }
; #pragma unroll
;         for (int cc = 0; cc < NCS; ++cc) {
;           const int c = (DUAL == 1) ? cc : st;
; #pragma unroll
;           for (int ks = 0; ks < 2; ++ks) {
;             if (st == 0) { s0 = MFMA(ka[cc][ks], qa[c][ks], s0); s1 = MFMA(kb[cc][ks], qa[c][ks], s1); }
;             else         { s0 = MFMA(ka[cc][ks], qb[c][ks], s0); s1 = MFMA(kb[cc][ks], qb[c][ks], s1); }
;           }
;         }
.LBB0_335:
	v_lshl_or_b32 v66, s31, 6, v207
	s_xor_b64 s[2:3], s[8:9], -1
	v_mad_u32_u24 v167, v66, s33, v161
	v_lshl_add_u32 v211, s31, 7, v210
	ds_read_b128 v[66:69], v167
	ds_read_b128 v[170:173], v167 offset:32
	ds_read_b128 v[70:73], v167 offset:4608
	ds_read_b128 v[174:177], v167 offset:4640
	ds_read_b128 v[178:181], v167 offset:64
	ds_read_b128 v[182:185], v167 offset:96
	ds_read_b128 v[186:189], v167 offset:4672
	ds_read_b128 v[190:193], v167 offset:4704
	s_waitcnt lgkmcnt(7)
	v_mfma_f32_32x32x16_bf16 v[82:97], v[66:69], v[114:117], 0
	s_waitcnt lgkmcnt(5)
	v_mfma_f32_32x32x16_bf16 v[66:81], v[70:73], v[114:117], 0
	v_mfma_f32_32x32x16_bf16 v[82:97], v[170:173], v[122:125], v[82:97]
	s_waitcnt lgkmcnt(4)
	v_mfma_f32_32x32x16_bf16 v[66:81], v[174:177], v[122:125], v[66:81]
	s_waitcnt lgkmcnt(3)
	v_mfma_f32_32x32x16_bf16 v[82:97], v[178:181], v[130:133], v[82:97]
	s_waitcnt lgkmcnt(1)
	v_mfma_f32_32x32x16_bf16 v[66:81], v[186:189], v[130:133], v[66:81]
	v_mfma_f32_32x32x16_bf16 v[82:97], v[182:185], v[138:141], v[82:97]
	s_waitcnt lgkmcnt(0)
	v_mfma_f32_32x32x16_bf16 v[66:81], v[190:193], v[138:141], v[66:81]
	s_nop 9
	v_exp_f32_e32 v166, v82
	v_exp_f32_e32 v181, v84
	v_exp_f32_e32 v183, v85
	v_exp_f32_e32 v185, v86
	v_exp_f32_e32 v187, v87
	v_exp_f32_e32 v193, v88
	v_exp_f32_e32 v182, v89
	v_exp_f32_e32 v171, v66
	v_exp_f32_e32 v66, v83
	ds_read_b128 v[82:85], v211 offset:26624
	ds_read_b128 v[188:191], v211 offset:26656
	ds_read_b128 v[174:177], v211 offset:35328
	v_cvt_pk_bf16_f32 v87, v181, v183
	v_cvt_pk_bf16_f32 v86, v166, v66
	v_cvt_pk_bf16_f32 v88, v185, v187
	v_cvt_pk_bf16_f32 v89, v193, v182
	v_exp_f32_e32 v173, v67
	v_exp_f32_e32 v186, v90
	s_waitcnt lgkmcnt(2)
	v_mfma_f32_32x32x16_bf16 v[18:33], v[82:85], v[86:89], v[18:33]
	ds_read_b128 v[82:85], v211 offset:35360
	v_exp_f32_e32 v184, v91
	v_exp_f32_e32 v180, v92
	v_exp_f32_e32 v172, v93
	v_exp_f32_e32 v170, v94
	v_exp_f32_e32 v178, v95
	v_add_f32_e32 v67, v166, v171
	s_waitcnt lgkmcnt(1)
	v_mfma_f32_32x32x16_bf16 v[2:17], v[174:177], v[86:89], v[2:17]
	v_exp_f32_e32 v176, v96
	v_exp_f32_e32 v174, v97
	v_add_f32_e32 v67, 0, v67
	v_add_f32_e32 v179, v66, v173
	v_exp_f32_e32 v166, v68
	v_cvt_pk_bf16_f32 v86, v186, v184
	v_cvt_pk_bf16_f32 v87, v180, v172
	v_cvt_pk_bf16_f32 v88, v170, v178
	v_cvt_pk_bf16_f32 v89, v176, v174
	v_add_f32_e32 v90, v179, v67
	v_exp_f32_e32 v92, v69
	ds_read_b128 v[66:69], v211 offset:26688
	v_mfma_f32_32x32x16_bf16 v[18:33], v[188:191], v[86:89], v[18:33]
	v_exp_f32_e32 v93, v70
	v_exp_f32_e32 v94, v71
	v_exp_f32_e32 v95, v72
	v_exp_f32_e32 v204, v73
	v_cvt_pk_bf16_f32 v70, v171, v173
	v_cvt_pk_bf16_f32 v71, v166, v92
	v_cvt_pk_bf16_f32 v72, v93, v94
	s_waitcnt lgkmcnt(1)
	v_mfma_f32_32x32x16_bf16 v[2:17], v[82:85], v[86:89], v[2:17]
	ds_read_b128 v[82:85], v211 offset:35392
	ds_read_b128 v[86:89], v211 offset:26720
	v_cvt_pk_bf16_f32 v73, v95, v204
	v_exp_f32_e32 v188, v74
	v_exp_f32_e32 v192, v75
	v_exp_f32_e32 v190, v76
	v_exp_f32_e32 v196, v77
	v_exp_f32_e32 v194, v78
	s_waitcnt lgkmcnt(2)
	v_mfma_f32_32x32x16_bf16 v[18:33], v[66:69], v[70:73], v[18:33]
	ds_read_b128 v[66:69], v211 offset:35424
	v_exp_f32_e32 v202, v79
	v_exp_f32_e32 v200, v80
	v_exp_f32_e32 v198, v81
	v_add_f32_e32 v91, v181, v166
	v_add_f32_e32 v90, v91, v90
	v_add_f32_e32 v74, v183, v92
	s_waitcnt lgkmcnt(2)
	v_mfma_f32_32x32x16_bf16 v[2:17], v[82:85], v[70:73], v[2:17]
	v_cvt_pk_bf16_f32 v70, v188, v192
	v_cvt_pk_bf16_f32 v71, v190, v196
	v_cvt_pk_bf16_f32 v72, v194, v202
	v_cvt_pk_bf16_f32 v73, v200, v198
	v_add_f32_e32 v74, v74, v90
	v_add_f32_e32 v75, v185, v93
	v_add_f32_e32 v74, v75, v74
	s_waitcnt lgkmcnt(1)
	v_mfma_f32_32x32x16_bf16 v[18:33], v[86:89], v[70:73], v[18:33]
	v_add_f32_e32 v75, v187, v94
	v_add_f32_e32 v166, v75, v74
	v_add_f32_e32 v212, v193, v95
	s_waitcnt lgkmcnt(0)
	v_mfma_f32_32x32x16_bf16 v[2:17], v[66:69], v[70:73], v[2:17]
	ds_read_b128 v[66:69], v167
	ds_read_b128 v[216:219], v167 offset:32
	ds_read_b128 v[82:85], v167 offset:4608
	ds_read_b128 v[220:223], v167 offset:4640
	ds_read_b128 v[224:227], v167 offset:64
	ds_read_b128 v[236:239], v167 offset:96
	ds_read_b128 v[242:245], v167 offset:4672
	ds_read_b128 v[246:249], v167 offset:4704
	s_waitcnt lgkmcnt(7)
	v_mfma_f32_32x32x16_bf16 v[66:81], v[66:69], v[118:121], 0
	s_mov_b32 s31, 1
	s_mov_b64 s[8:9], 0
	s_mov_b64 s[28:29], -1
	s_and_b64 vcc, exec, s[2:3]
	s_waitcnt lgkmcnt(5)
; template <int DUAL, bool BOUND> ...
;     ...
;     if (BOUND) {
;       float ps = 0.f;
; #pragma unroll
;       for (int i = 0; i < 16; ++i) {
;         s0[i] = fexp2(s0[i]);
;         s1[i] = fexp2(s1[i]);
;         ps += s0[i] + s1[i];
;       }
;       l += ps;
;     } else {
;       float mx = fmaxf(s0[0], s1[0]);
; #pragma unroll
;       for (int i = 1; i < 16; ++i) mx = fmaxf(mx, fmaxf(s0[i], s1[i]));
;       mx = fmaxf(mx, xhalf(mx));
;       const float mnew = fmaxf(m, mx);
;       const float alpha = fexp2(m - mnew);
;       m = mnew;
;       float ps = 0.f;
; #pragma unroll
;       for (int i = 0; i < 16; ++i) {
;         s0[i] = fexp2(s0[i] - mnew);
;         s1[i] = fexp2(s1[i] - mnew);
;         ps += s0[i] + s1[i];
;       }
;       l = l * alpha + ps;
; #pragma unroll
;       for (int i = 0; i < 16; ++i) { o0[i] *= alpha; o1[i] *= alpha; }
;     }
;     const char* vb0 = cur + A_VOFF + r * V_ROW + hf * 128 + 16 * h;
; #pragma unroll
;     for (int kb = 0; kb < 2; ++kb)
; #pragma unroll
;       for (int s = 0; s < 2; ++s) {
;         uint4 pu;
;     ...
;     for (int hf = 0; hf < 2; ++hf) {
;       if (hf == 1) gload_v(more ? t + 1 : t);
;       const char* kb0 = cur + (hf * 64 + r) * KSTR + h * 16;
;       f32x16 s0, s1;
;       const float rel = (float)(qpos - t * 128 - hf * 64 - 4 * h);
; #pragma unroll
;       for (int st = 0; st < 2; ++st) {
;         constexpr int NCS = (DUAL == 1) ? 2 : 1;
;         bf16x8 ka[NCS][2], kb[NCS][2];
;         __builtin_amdgcn_sched_barrier(0);
; #pragma unroll
;         for (int cc = 0; cc < NCS; ++cc) {
;           const int c = (DUAL == 1) ? cc : st;
; #pragma unroll
;           for (int ks = 0; ks < 2; ++ks) {
;             ka[cc][ks] = *(const bf16x8*)(kb0 + c * 64 + ks * 32);
;             kb[cc][ks] = *(const bf16x8*)(kb0 + 32 * KSTR + c * 64 + ks * 32);
;           }
;         }
;         __builtin_amdgcn_sched_barrier(0);
; #pragma unroll
;         for (int i = 0; i < 16; ++i) { s0[i] = 0.f; s1[i] = 0.f; }
; #pragma unroll
;         for (int cc = 0; cc < NCS; ++cc) {
;           const int c = (DUAL == 1) ? cc : st;
; #pragma unroll
;           for (int ks = 0; ks < 2; ++ks) {
;             if (st == 0) { s0 = MFMA(ka[cc][ks], qa[c][ks], s0); s1 = MFMA(kb[cc][ks], qa[c][ks], s1); }
;             else         { s0 = MFMA(ka[cc][ks], qb[c][ks], s0); s1 = MFMA(kb[cc][ks], qb[c][ks], s1); }
;           }
;         }
	v_mfma_f32_32x32x16_bf16 v[82:97], v[82:85], v[118:121], 0
	v_mfma_f32_32x32x16_bf16 v[66:81], v[216:219], v[126:129], v[66:81]
	s_waitcnt lgkmcnt(4)
	v_mfma_f32_32x32x16_bf16 v[82:97], v[220:223], v[126:129], v[82:97]
	s_waitcnt lgkmcnt(3)
	v_mfma_f32_32x32x16_bf16 v[66:81], v[224:227], v[134:137], v[66:81]
	s_waitcnt lgkmcnt(1)
	v_mfma_f32_32x32x16_bf16 v[82:97], v[242:245], v[134:137], v[82:97]
	v_mfma_f32_32x32x16_bf16 v[66:81], v[236:239], v[142:145], v[66:81]
	s_waitcnt lgkmcnt(0)
	v_mfma_f32_32x32x16_bf16 v[82:97], v[246:249], v[142:145], v[82:97]
	s_nop 9
	v_exp_f32_e32 v171, v66
	v_exp_f32_e32 v175, v71
	v_exp_f32_e32 v177, v72
	v_exp_f32_e32 v183, v73
	v_exp_f32_e32 v187, v74
	v_exp_f32_e32 v185, v75
	v_exp_f32_e32 v181, v76
	v_exp_f32_e32 v216, v82
	v_exp_f32_e32 v82, v67
	v_exp_f32_e32 v217, v83
	v_exp_f32_e32 v83, v68
	v_exp_f32_e32 v218, v84
	v_exp_f32_e32 v84, v69
	v_exp_f32_e32 v219, v85
	v_add_f32_e32 v66, v171, v216
	v_exp_f32_e32 v85, v70
	v_exp_f32_e32 v86, v86
	v_add_f32_e32 v66, 0, v66
	v_add_f32_e32 v67, v82, v217
	v_exp_f32_e32 v87, v87
	v_add_f32_e32 v66, v67, v66
	v_add_f32_e32 v67, v83, v218
	v_add_f32_e32 v66, v67, v66
	v_add_f32_e32 v67, v84, v219
	v_add_f32_e32 v66, v67, v66
	v_add_f32_e32 v67, v85, v86
	v_add_f32_e32 v66, v67, v66
	v_add_f32_e32 v67, v175, v87
	v_add_f32_e32 v167, v67, v66
	ds_read_b128 v[66:69], v211 offset:26624
	v_exp_f32_e32 v88, v88
	v_cvt_pk_bf16_f32 v70, v171, v82
	v_cvt_pk_bf16_f32 v71, v83, v84
	v_cvt_pk_bf16_f32 v72, v85, v175
	v_cvt_pk_bf16_f32 v73, v177, v183
	v_exp_f32_e32 v173, v77
	ds_read_b128 v[74:77], v211 offset:26656
	ds_read_b128 v[82:85], v211 offset:35328
	s_waitcnt lgkmcnt(2)
	v_mfma_f32_32x32x16_bf16 v[34:49], v[66:69], v[70:73], v[34:49]
	v_add_f32_e32 v213, v177, v88
	v_exp_f32_e32 v171, v78
	v_exp_f32_e32 v179, v79
	v_exp_f32_e32 v177, v80
	v_exp_f32_e32 v175, v81
	v_exp_f32_e32 v205, v89
	v_exp_f32_e32 v189, v90
	v_exp_f32_e32 v193, v91
	ds_read_b128 v[66:69], v211 offset:35360
	s_waitcnt lgkmcnt(1)
	v_mfma_f32_32x32x16_bf16 v[50:65], v[82:85], v[70:73], v[50:65]
	v_cvt_pk_bf16_f32 v70, v187, v185
	v_cvt_pk_bf16_f32 v71, v181, v173
	v_cvt_pk_bf16_f32 v72, v171, v179
	v_cvt_pk_bf16_f32 v73, v177, v175
	v_add_f32_e64 v78, v212, v166
	v_add_f32_e64 v79, v213, v167
	v_exp_f32_e32 v191, v92
	v_exp_f32_e32 v197, v93
	v_mfma_f32_32x32x16_bf16 v[34:49], v[74:77], v[70:73], v[34:49]
	v_add_f32_e64 v74, v182, v204
	v_add_f32_e64 v75, v183, v205
	v_add_f32_e64 v76, v186, v188
	v_add_f32_e64 v77, v187, v189
	v_add_f32_e64 v74, v74, v78
	v_add_f32_e64 v75, v75, v79
	v_exp_f32_e32 v195, v94
	v_add_f32_e32 v74, v76, v74
	v_add_f32_e32 v75, v77, v75
	v_add_f32_e32 v76, v184, v192
	v_add_f32_e32 v77, v185, v193
	v_add_f32_e32 v84, v180, v190
	v_add_f32_e32 v85, v181, v191
	v_add_f32_e32 v82, v76, v74
	v_add_f32_e32 v83, v77, v75
	ds_read_b128 v[74:77], v211 offset:26688
	s_waitcnt lgkmcnt(1)
	v_mfma_f32_32x32x16_bf16 v[50:65], v[66:69], v[70:73], v[50:65]
	v_cvt_pk_bf16_f32 v66, v216, v217
	v_cvt_pk_bf16_f32 v67, v218, v219
	v_cvt_pk_bf16_f32 v68, v86, v87
	v_cvt_pk_bf16_f32 v69, v88, v205
	ds_read_b128 v[70:73], v211 offset:35392
	ds_read_b128 v[78:81], v211 offset:26720
	v_exp_f32_e32 v203, v95
	v_exp_f32_e32 v201, v96
	s_waitcnt lgkmcnt(2)
	v_mfma_f32_32x32x16_bf16 v[34:49], v[74:77], v[66:69], v[34:49]
	v_add_f32_e64 v74, v84, v82
	v_add_f32_e64 v75, v85, v83
	v_add_f32_e64 v76, v172, v196
	v_add_f32_e64 v77, v173, v197
	v_exp_f32_e32 v199, v97
	v_add_f32_e32 v74, v76, v74
	v_add_f32_e32 v75, v77, v75
	v_add_f32_e32 v76, v170, v194
	v_add_f32_e32 v77, v171, v195
	v_add_f32_e32 v84, v178, v202
	v_add_f32_e32 v85, v179, v203
	v_add_f32_e32 v82, v76, v74
	v_add_f32_e32 v83, v77, v75
	ds_read_b128 v[74:77], v211 offset:35424
	s_waitcnt lgkmcnt(2)
	v_mfma_f32_32x32x16_bf16 v[50:65], v[70:73], v[66:69], v[50:65]
	v_add_f32_e64 v66, v84, v82
	v_add_f32_e64 v67, v85, v83
	v_add_f32_e64 v68, v176, v200
	v_add_f32_e64 v69, v177, v201
	v_add_f32_e64 v72, v174, v198
	v_add_f32_e64 v73, v175, v199
	v_add_f32_e32 v70, v68, v66
	v_add_f32_e32 v71, v69, v67
	v_cvt_pk_bf16_f32 v66, v189, v193
	v_cvt_pk_bf16_f32 v67, v191, v197
	v_cvt_pk_bf16_f32 v68, v195, v203
	v_cvt_pk_bf16_f32 v69, v201, v199
	v_add_f32_e32 v70, v72, v70
	v_add_f32_e32 v71, v73, v71
	s_waitcnt lgkmcnt(1)
	v_mfma_f32_32x32x16_bf16 v[34:49], v[78:81], v[66:69], v[34:49]
	v_add_f32_e64 v158, v158, v70
	v_add_f32_e64 v159, v159, v71
	s_waitcnt lgkmcnt(0)
	v_mfma_f32_32x32x16_bf16 v[50:65], v[74:77], v[66:69], v[50:65]
	s_cbranch_vccnz .LBB0_338

; #define MFMA(a, b, c) __builtin_amdgcn_mfma_f32_32x32x16_bf16((a), (b), (c), 0, 0, 0)
; template <bool BOUND> ...
;     ...
;   auto softmax_pv = [&](const char* cur, int hf, f32x16& s0, f32x16& s1, float& m, float& l, f32x16& o0, f32x16& o1) {
;     if (BOUND) {
;       float ps = 0.f;
; #pragma unroll
;       for (int i = 0; i < 16; ++i) {
;         s0[i] = fexp2(s0[i]);
;         s1[i] = fexp2(s1[i]);
;         ps += s0[i] + s1[i];
;       }
;       l += ps;
;     } else {
;       float mx = fmaxf(s0[0], s1[0]);
; #pragma unroll
;       for (int i = 1; i < 16; ++i) mx = fmaxf(mx, fmaxf(s0[i], s1[i]));
;       mx = fmaxf(mx, xhalf(mx));
;       const float mnew = fmaxf(m, mx);
;       const float alpha = fexp2(m - mnew);
;       m = mnew;
;       float ps = 0.f;
; #pragma unroll
;       for (int i = 0; i < 16; ++i) {
;         s0[i] = fexp2(s0[i] - mnew);
;         s1[i] = fexp2(s1[i] - mnew);
;         ps += s0[i] + s1[i];
;       }
;       l = l * alpha + ps;
; #pragma unroll
;       for (int i = 0; i < 16; ++i) { o0[i] *= alpha; o1[i] *= alpha; }
;     }
;     const char* vb0 = cur + A_VOFF + r * V_ROW + hf * 128 + 16 * h;
; #pragma unroll
;     for (int kb = 0; kb < 2; ++kb)
; #pragma unroll
;       for (int s = 0; s < 2; ++s) {
;         uint4 pu;
;         if (kb == 0) {
;     ...
;     for (int hf = 0; hf < 2; ++hf) {
;       if (hf == 1) gload_v(more ? t + 1 : t);
;       const char* kb0 = cur + (hf * 64 + r) * KSTR + h * 16;
;       f32x16 s0, s1;
; #pragma unroll
;       for (int st = 0; st < 2; ++st) {
;         __builtin_amdgcn_sched_barrier(0);
; #pragma unroll
;         for (int i = 0; i < 16; ++i) { s0[i] = 0.f; s1[i] = 0.f; }
; #pragma unroll
;         for (int c = 0; c < 3; ++c) {
;           bf16x8 ka[2], kb[2];
; #pragma unroll
;           for (int ks = 0; ks < 2; ++ks) {
;             ka[ks] = *(const bf16x8*)(kb0 + c * 64 + ks * 32);
;             kb[ks] = *(const bf16x8*)(kb0 + 32 * KSTR + c * 64 + ks * 32);
;           }
; #pragma unroll
;           for (int ks = 0; ks < 2; ++ks) {
;             if (st == 0) { s0 = MFMA(ka[ks], qa[c][ks], s0); s1 = MFMA(kb[ks], qa[c][ks], s1); }
;             else         { s0 = MFMA(ka[ks], qb[c][ks], s0); s1 = MFMA(kb[ks], qb[c][ks], s1); }
;           }
;         }
;         if (st == 0) softmax_pv(cur, hf, s0, s1, mA, lA, oA0, oA1);
;         else         softmax_pv(cur, hf, s0, s1, mB, lB, oB0, oB1);
.LBB0_374:
	v_lshl_or_b32 v66, s31, 6, v243
	s_xor_b64 s[2:3], s[8:9], -1
	v_mad_u32_u24 v167, v66, s37, v185
	v_lshl_add_u32 v247, s31, 7, v246
	ds_read_b128 v[66:69], v167
	ds_read_b128 v[192:195], v167 offset:32
	s_waitcnt lgkmcnt(1)
	v_mfma_f32_32x32x16_bf16 v[82:97], v[66:69], v[118:121], 0
	ds_read_b128 v[66:69], v167 offset:6656
	ds_read_b128 v[196:199], v167 offset:6688
	s_waitcnt lgkmcnt(1)
	v_mfma_f32_32x32x16_bf16 v[66:81], v[66:69], v[118:121], 0
	v_mfma_f32_32x32x16_bf16 v[82:97], v[192:195], v[126:129], v[82:97]
	s_waitcnt lgkmcnt(0)
	v_mfma_f32_32x32x16_bf16 v[66:81], v[196:199], v[126:129], v[66:81]
	ds_read_b128 v[192:195], v167 offset:64
	ds_read_b128 v[196:199], v167 offset:96
	s_waitcnt lgkmcnt(1)
	v_mfma_f32_32x32x16_bf16 v[82:97], v[192:195], v[134:137], v[82:97]
	ds_read_b128 v[192:195], v167 offset:6720
	ds_read_b128 v[200:203], v167 offset:6752
	s_waitcnt lgkmcnt(1)
	v_mfma_f32_32x32x16_bf16 v[66:81], v[192:195], v[134:137], v[66:81]
	v_mfma_f32_32x32x16_bf16 v[82:97], v[196:199], v[142:145], v[82:97]
	ds_read_b128 v[192:195], v167 offset:128
	ds_read_b128 v[196:199], v167 offset:160
	s_waitcnt lgkmcnt(2)
	v_mfma_f32_32x32x16_bf16 v[66:81], v[200:203], v[142:145], v[66:81]
	s_waitcnt lgkmcnt(1)
	v_mfma_f32_32x32x16_bf16 v[82:97], v[192:195], v[150:153], v[82:97]
	ds_read_b128 v[192:195], v167 offset:6784
	ds_read_b128 v[200:203], v167 offset:6816
	s_waitcnt lgkmcnt(1)
	v_mfma_f32_32x32x16_bf16 v[66:81], v[192:195], v[150:153], v[66:81]
	v_mfma_f32_32x32x16_bf16 v[82:97], v[196:199], v[158:161], v[82:97]
	s_waitcnt lgkmcnt(0)
	v_mfma_f32_32x32x16_bf16 v[66:81], v[200:203], v[158:161], v[66:81]
	s_nop 9
	v_exp_f32_e32 v166, v82
	v_exp_f32_e32 v203, v84
	v_exp_f32_e32 v205, v85
	v_exp_f32_e32 v207, v86
	v_exp_f32_e32 v209, v87
	v_exp_f32_e32 v215, v88
	v_exp_f32_e32 v204, v89
	v_exp_f32_e32 v193, v66
	v_exp_f32_e32 v66, v83
	ds_read_b128 v[82:85], v247 offset:26624
	ds_read_b128 v[210:213], v247 offset:26656
	ds_read_b128 v[196:199], v247 offset:35328
	v_cvt_pk_bf16_f32 v87, v203, v205
	v_cvt_pk_bf16_f32 v86, v166, v66
	v_cvt_pk_bf16_f32 v88, v207, v209
	v_cvt_pk_bf16_f32 v89, v215, v204
	v_exp_f32_e32 v195, v67
	v_exp_f32_e32 v208, v90
	s_waitcnt lgkmcnt(2)
	v_mfma_f32_32x32x16_bf16 v[34:49], v[82:85], v[86:89], v[34:49]
	ds_read_b128 v[82:85], v247 offset:35360
	v_exp_f32_e32 v206, v91
	v_exp_f32_e32 v202, v92
	v_exp_f32_e32 v194, v93
	v_exp_f32_e32 v192, v94
	v_exp_f32_e32 v200, v95
	v_add_f32_e32 v67, v166, v193
	s_waitcnt lgkmcnt(1)
	v_mfma_f32_32x32x16_bf16 v[2:17], v[196:199], v[86:89], v[2:17]
	v_exp_f32_e32 v198, v96
	v_exp_f32_e32 v196, v97
	v_add_f32_e32 v67, 0, v67
	v_add_f32_e32 v201, v66, v195
	v_exp_f32_e32 v166, v68
	v_cvt_pk_bf16_f32 v86, v208, v206
	v_cvt_pk_bf16_f32 v87, v202, v194
	v_cvt_pk_bf16_f32 v88, v192, v200
	v_cvt_pk_bf16_f32 v89, v198, v196
	v_add_f32_e32 v90, v201, v67
	v_exp_f32_e32 v92, v69
	ds_read_b128 v[66:69], v247 offset:26688
	v_mfma_f32_32x32x16_bf16 v[34:49], v[210:213], v[86:89], v[34:49]
	v_exp_f32_e32 v93, v70
	v_exp_f32_e32 v94, v71
	v_exp_f32_e32 v95, v72
	v_exp_f32_e32 v226, v73
	v_cvt_pk_bf16_f32 v70, v193, v195
	v_cvt_pk_bf16_f32 v71, v166, v92
	v_cvt_pk_bf16_f32 v72, v93, v94
	s_waitcnt lgkmcnt(1)
	v_mfma_f32_32x32x16_bf16 v[2:17], v[82:85], v[86:89], v[2:17]
	ds_read_b128 v[82:85], v247 offset:35392
	ds_read_b128 v[86:89], v247 offset:26720
	v_cvt_pk_bf16_f32 v73, v95, v226
	v_exp_f32_e32 v210, v74
	v_exp_f32_e32 v214, v75
	v_exp_f32_e32 v212, v76
	v_exp_f32_e32 v218, v77
	v_exp_f32_e32 v216, v78
	s_waitcnt lgkmcnt(2)
	v_mfma_f32_32x32x16_bf16 v[34:49], v[66:69], v[70:73], v[34:49]
	ds_read_b128 v[66:69], v247 offset:35424
	v_exp_f32_e32 v224, v79
	v_exp_f32_e32 v222, v80
	v_exp_f32_e32 v220, v81
	v_add_f32_e32 v91, v203, v166
	v_add_f32_e32 v90, v91, v90
	v_add_f32_e32 v74, v205, v92
	s_waitcnt lgkmcnt(2)
	v_mfma_f32_32x32x16_bf16 v[2:17], v[82:85], v[70:73], v[2:17]
	v_cvt_pk_bf16_f32 v70, v210, v214
	v_cvt_pk_bf16_f32 v71, v212, v218
	v_cvt_pk_bf16_f32 v72, v216, v224
	v_cvt_pk_bf16_f32 v73, v222, v220
	v_add_f32_e32 v74, v74, v90
	v_add_f32_e32 v75, v207, v93
	v_add_f32_e32 v74, v75, v74
	s_waitcnt lgkmcnt(1)
	v_mfma_f32_32x32x16_bf16 v[34:49], v[86:89], v[70:73], v[34:49]
	v_add_f32_e32 v75, v209, v94
	v_add_f32_e32 v248, v75, v74
	v_add_f32_e32 v166, v215, v95
	s_waitcnt lgkmcnt(0)
	v_mfma_f32_32x32x16_bf16 v[2:17], v[66:69], v[70:73], v[2:17]
	ds_read_b128 v[66:69], v167
	ds_read_b128 v[236:239], v167 offset:32
	ds_read_b128 v[82:85], v167 offset:6656
	s_mov_b32 s31, 1
	s_mov_b64 s[8:9], 0
	s_waitcnt lgkmcnt(2)
	v_mfma_f32_32x32x16_bf16 v[66:81], v[66:69], v[122:125], 0
	s_mov_b64 s[28:29], -1
	s_and_b64 vcc, exec, s[2:3]
	s_waitcnt lgkmcnt(1)
	v_mfma_f32_32x32x16_bf16 v[66:81], v[236:239], v[130:133], v[66:81]
	ds_read_b128 v[236:239], v167 offset:6688
	s_waitcnt lgkmcnt(1)
	v_mfma_f32_32x32x16_bf16 v[82:97], v[82:85], v[122:125], 0
	s_waitcnt lgkmcnt(0)
	v_mfma_f32_32x32x16_bf16 v[82:97], v[236:239], v[130:133], v[82:97]
	ds_read_b128 v[236:239], v167 offset:64
	s_waitcnt lgkmcnt(0)
; #define MFMA(a, b, c) __builtin_amdgcn_mfma_f32_32x32x16_bf16((a), (b), (c), 0, 0, 0)
; template <bool BOUND> ...
;     ...
;   auto softmax_pv = [&](const char* cur, int hf, f32x16& s0, f32x16& s1, float& m, float& l, f32x16& o0, f32x16& o1) {
;     if (BOUND) {
;       float ps = 0.f;
; #pragma unroll
;       for (int i = 0; i < 16; ++i) {
;         s0[i] = fexp2(s0[i]);
;         s1[i] = fexp2(s1[i]);
;         ps += s0[i] + s1[i];
;       }
;       l += ps;
;     } else {
;       float mx = fmaxf(s0[0], s1[0]);
; #pragma unroll
;       for (int i = 1; i < 16; ++i) mx = fmaxf(mx, fmaxf(s0[i], s1[i]));
;       mx = fmaxf(mx, xhalf(mx));
;       const float mnew = fmaxf(m, mx);
;       const float alpha = fexp2(m - mnew);
;       m = mnew;
;       float ps = 0.f;
; #pragma unroll
;       for (int i = 0; i < 16; ++i) {
;         s0[i] = fexp2(s0[i] - mnew);
;         s1[i] = fexp2(s1[i] - mnew);
;         ps += s0[i] + s1[i];
;       }
;       l = l * alpha + ps;
; #pragma unroll
;       for (int i = 0; i < 16; ++i) { o0[i] *= alpha; o1[i] *= alpha; }
;     }
;     const char* vb0 = cur + A_VOFF + r * V_ROW + hf * 128 + 16 * h;
; #pragma unroll
;     for (int kb = 0; kb < 2; ++kb)
; #pragma unroll
;       for (int s = 0; s < 2; ++s) {
;         uint4 pu;
;         if (kb == 0) {
;     ...
;     for (int hf = 0; hf < 2; ++hf) {
;       if (hf == 1) gload_v(more ? t + 1 : t);
;       const char* kb0 = cur + (hf * 64 + r) * KSTR + h * 16;
;       f32x16 s0, s1;
; #pragma unroll
;       for (int st = 0; st < 2; ++st) {
;         __builtin_amdgcn_sched_barrier(0);
; #pragma unroll
;         for (int i = 0; i < 16; ++i) { s0[i] = 0.f; s1[i] = 0.f; }
; #pragma unroll
;         for (int c = 0; c < 3; ++c) {
;           bf16x8 ka[2], kb[2];
; #pragma unroll
;           for (int ks = 0; ks < 2; ++ks) {
;             ka[ks] = *(const bf16x8*)(kb0 + c * 64 + ks * 32);
;             kb[ks] = *(const bf16x8*)(kb0 + 32 * KSTR + c * 64 + ks * 32);
;           }
; #pragma unroll
;           for (int ks = 0; ks < 2; ++ks) {
;             if (st == 0) { s0 = MFMA(ka[ks], qa[c][ks], s0); s1 = MFMA(kb[ks], qa[c][ks], s1); }
;             else         { s0 = MFMA(ka[ks], qb[c][ks], s0); s1 = MFMA(kb[ks], qb[c][ks], s1); }
;           }
;         }
;         if (st == 0) softmax_pv(cur, hf, s0, s1, mA, lA, oA0, oA1);
;         else         softmax_pv(cur, hf, s0, s1, mB, lB, oB0, oB1);
	v_mfma_f32_32x32x16_bf16 v[66:81], v[236:239], v[138:141], v[66:81]
	ds_read_b128 v[236:239], v167 offset:6720
	s_waitcnt lgkmcnt(0)
	v_mfma_f32_32x32x16_bf16 v[82:97], v[236:239], v[138:141], v[82:97]
	ds_read_b128 v[236:239], v167 offset:96
	s_waitcnt lgkmcnt(0)
	v_mfma_f32_32x32x16_bf16 v[66:81], v[236:239], v[146:149], v[66:81]
	ds_read_b128 v[236:239], v167 offset:6752
	s_waitcnt lgkmcnt(0)
	v_mfma_f32_32x32x16_bf16 v[82:97], v[236:239], v[146:149], v[82:97]
	ds_read_b128 v[236:239], v167 offset:128
	s_waitcnt lgkmcnt(0)
	v_mfma_f32_32x32x16_bf16 v[66:81], v[236:239], v[154:157], v[66:81]
	ds_read_b128 v[236:239], v167 offset:6784
	s_waitcnt lgkmcnt(0)
	v_mfma_f32_32x32x16_bf16 v[82:97], v[236:239], v[154:157], v[82:97]
	ds_read_b128 v[236:239], v167 offset:160
	s_waitcnt lgkmcnt(0)
	v_mfma_f32_32x32x16_bf16 v[66:81], v[236:239], v[162:165], v[66:81]
	ds_read_b128 v[236:239], v167 offset:6816
	s_waitcnt lgkmcnt(0)
	v_mfma_f32_32x32x16_bf16 v[82:97], v[236:239], v[162:165], v[82:97]
	s_nop 8
	v_exp_f32_e32 v193, v66
	v_exp_f32_e32 v197, v71
	v_exp_f32_e32 v199, v72
	v_exp_f32_e32 v205, v73
	v_exp_f32_e32 v209, v74
	v_exp_f32_e32 v207, v75
	v_exp_f32_e32 v203, v76
	v_exp_f32_e32 v236, v82
	v_exp_f32_e32 v82, v67
	v_exp_f32_e32 v237, v83
	v_exp_f32_e32 v83, v68
	v_exp_f32_e32 v238, v84
	v_exp_f32_e32 v84, v69
	v_exp_f32_e32 v239, v85
	v_add_f32_e32 v66, v193, v236
	v_exp_f32_e32 v85, v70
	v_exp_f32_e32 v86, v86
	v_add_f32_e32 v66, 0, v66
	v_add_f32_e32 v67, v82, v237
	v_exp_f32_e32 v87, v87
	v_add_f32_e32 v66, v67, v66
	v_add_f32_e32 v67, v83, v238
	v_add_f32_e32 v66, v67, v66
	v_add_f32_e32 v67, v84, v239
	v_add_f32_e32 v66, v67, v66
	v_add_f32_e32 v67, v85, v86
	v_add_f32_e32 v66, v67, v66
	v_add_f32_e32 v67, v197, v87
	v_add_f32_e32 v249, v67, v66
	ds_read_b128 v[66:69], v247 offset:26624
	v_exp_f32_e32 v88, v88
	v_cvt_pk_bf16_f32 v70, v193, v82
	v_cvt_pk_bf16_f32 v71, v83, v84
	v_cvt_pk_bf16_f32 v72, v85, v197
	v_cvt_pk_bf16_f32 v73, v199, v205
	v_exp_f32_e32 v195, v77
	ds_read_b128 v[74:77], v247 offset:26656
	ds_read_b128 v[82:85], v247 offset:35328
	s_waitcnt lgkmcnt(2)
	v_mfma_f32_32x32x16_bf16 v[50:65], v[66:69], v[70:73], v[50:65]
	v_add_f32_e32 v167, v199, v88
	v_exp_f32_e32 v193, v78
	v_exp_f32_e32 v201, v79
	v_exp_f32_e32 v199, v80
	v_exp_f32_e32 v197, v81
	v_exp_f32_e32 v227, v89
	v_exp_f32_e32 v211, v90
	v_exp_f32_e32 v215, v91
	ds_read_b128 v[66:69], v247 offset:35360
	s_waitcnt lgkmcnt(1)
	v_mfma_f32_32x32x16_bf16 v[18:33], v[82:85], v[70:73], v[18:33]
	v_cvt_pk_bf16_f32 v70, v209, v207
	v_cvt_pk_bf16_f32 v71, v203, v195
	v_cvt_pk_bf16_f32 v72, v193, v201
	v_cvt_pk_bf16_f32 v73, v199, v197
	v_add_f32_e64 v78, v166, v248
	v_add_f32_e64 v79, v167, v249
	v_exp_f32_e32 v213, v92
	v_exp_f32_e32 v219, v93
	v_mfma_f32_32x32x16_bf16 v[50:65], v[74:77], v[70:73], v[50:65]
	v_add_f32_e64 v74, v204, v226
	v_add_f32_e64 v75, v205, v227
	v_add_f32_e64 v76, v208, v210
	v_add_f32_e64 v77, v209, v211
	v_add_f32_e64 v74, v74, v78
	v_add_f32_e64 v75, v75, v79
	v_exp_f32_e32 v217, v94
	v_add_f32_e32 v74, v76, v74
	v_add_f32_e32 v75, v77, v75
	v_add_f32_e32 v76, v206, v214
	v_add_f32_e32 v77, v207, v215
	v_add_f32_e32 v84, v202, v212
	v_add_f32_e32 v85, v203, v213
	v_add_f32_e32 v82, v76, v74
	v_add_f32_e32 v83, v77, v75
	ds_read_b128 v[74:77], v247 offset:26688
	s_waitcnt lgkmcnt(1)
	v_mfma_f32_32x32x16_bf16 v[18:33], v[66:69], v[70:73], v[18:33]
	v_cvt_pk_bf16_f32 v66, v236, v237
	v_cvt_pk_bf16_f32 v67, v238, v239
	v_cvt_pk_bf16_f32 v68, v86, v87
	v_cvt_pk_bf16_f32 v69, v88, v227
	ds_read_b128 v[70:73], v247 offset:35392
	ds_read_b128 v[78:81], v247 offset:26720
	v_exp_f32_e32 v225, v95
	v_exp_f32_e32 v223, v96
	s_waitcnt lgkmcnt(2)
	v_mfma_f32_32x32x16_bf16 v[50:65], v[74:77], v[66:69], v[50:65]
	v_add_f32_e64 v74, v84, v82
	v_add_f32_e64 v75, v85, v83
	v_add_f32_e64 v76, v194, v218
	v_add_f32_e64 v77, v195, v219
	v_exp_f32_e32 v221, v97
	v_add_f32_e32 v74, v76, v74
	v_add_f32_e32 v75, v77, v75
	v_add_f32_e32 v76, v192, v216
	v_add_f32_e32 v77, v193, v217
	v_add_f32_e32 v84, v200, v224
	v_add_f32_e32 v85, v201, v225
	v_add_f32_e32 v82, v76, v74
	v_add_f32_e32 v83, v77, v75
	ds_read_b128 v[74:77], v247 offset:35424
	s_waitcnt lgkmcnt(2)
	v_mfma_f32_32x32x16_bf16 v[18:33], v[70:73], v[66:69], v[18:33]
	v_add_f32_e64 v66, v84, v82
	v_add_f32_e64 v67, v85, v83
	v_add_f32_e64 v68, v198, v222
	v_add_f32_e64 v69, v199, v223
	v_add_f32_e64 v72, v196, v220
	v_add_f32_e64 v73, v197, v221
	v_add_f32_e32 v70, v68, v66
	v_add_f32_e32 v71, v69, v67
	v_cvt_pk_bf16_f32 v66, v211, v215
	v_cvt_pk_bf16_f32 v67, v213, v219
	v_cvt_pk_bf16_f32 v68, v217, v225
	v_cvt_pk_bf16_f32 v69, v223, v221
	v_add_f32_e32 v70, v72, v70
	v_add_f32_e32 v71, v73, v71
	s_waitcnt lgkmcnt(1)
	v_mfma_f32_32x32x16_bf16 v[50:65], v[78:81], v[66:69], v[50:65]
	v_add_f32_e64 v182, v182, v70
	v_add_f32_e64 v183, v183, v71
	s_waitcnt lgkmcnt(0)
	v_mfma_f32_32x32x16_bf16 v[18:33], v[74:77], v[66:69], v[18:33]
	s_cbranch_vccnz .LBB0_377
